# k05 + attention unit remap (workgroup walks consecutive key blocks: K/V re-read becomes an L2 hit)
# baseline (speedup 1.0000x reference)
.LBB0_695:
	v_readlane_b32 s10, v254, 5
	s_lshl_b32 s9, s10, 3
	s_lshl_b32 s0, s82, 3
	s_add_i32 s4, s9, 0x3fff
	v_readlane_b32 s11, v254, 6
	v_writelane_b32 v254, s0, 9
	s_add_u32 s0, s40, 0x1f700200
	s_addc_u32 s1, s41, 0
	v_writelane_b32 v254, s0, 10
	s_mov_b32 s15, s37
	s_movk_i32 s33, 0x2400
	v_writelane_b32 v254, s1, 11
	s_add_u32 s0, s40, 0x1f700400
	s_addc_u32 s1, s41, 0
	v_writelane_b32 v254, s0, 12
	v_mov_b32_e32 v129, 0
	v_mov_b32_e32 v146, 0x358637bd
	v_writelane_b32 v254, s1, 13
	s_add_u32 s0, s40, 0x1f700500
	s_addc_u32 s1, s41, 0
	v_writelane_b32 v254, s0, 14
	s_mov_b32 s53, 0x800000
	v_mov_b32_e32 v147, 0x1000
	v_writelane_b32 v254, s1, 15
	s_add_u32 s0, s40, 0x1f700600
	s_addc_u32 s1, s41, 0
	v_writelane_b32 v254, s0, 16
	v_mov_b32_e32 v148, 0x2000
	v_mov_b32_e32 v149, 1
	v_writelane_b32 v254, s1, 17
	s_add_u32 s0, s40, 0x1f700700
	s_addc_u32 s1, s41, 0
	v_writelane_b32 v254, s0, 18
	v_mov_b64_e32 v[130:131], 0x680
	v_mov_b64_e32 v[132:133], 0x67f
	v_writelane_b32 v254, s1, 19
	s_add_u32 s0, s40, 0x1f700800
	s_addc_u32 s1, s41, 0
	v_writelane_b32 v254, s0, 20
	v_mov_b32_e32 v151, 0xff800000
	v_mov_b32_e32 v152, 0x41b17218
	v_writelane_b32 v254, s1, 21
	s_add_u32 s0, s40, 0x1f700900
	s_addc_u32 s1, s41, 0
	v_writelane_b32 v254, s0, 22
	s_mov_b64 s[44:45], 0x80
	s_mov_b64 s[54:55], 0xcc00000
	v_writelane_b32 v254, s1, 23
	s_add_u32 s0, s40, 0x1f700a00
	s_addc_u32 s1, s41, 0
	v_writelane_b32 v254, s0, 24
	s_nop 1
	v_writelane_b32 v254, s1, 25
	s_add_u32 s0, s40, 0x1f700b00
	s_addc_u32 s1, s41, 0
	v_writelane_b32 v254, s0, 26
	s_nop 1
	v_writelane_b32 v254, s1, 27
	s_add_u32 s0, s40, 0x1f700c00
	s_addc_u32 s1, s41, 0
	v_writelane_b32 v254, s0, 28
	s_nop 1
	v_writelane_b32 v254, s1, 29
	s_add_u32 s0, s40, 0x1f700d00
	s_addc_u32 s1, s41, 0
	v_writelane_b32 v254, s0, 30
	s_nop 1
	v_writelane_b32 v254, s1, 31
	s_add_u32 s0, s40, 0x1f700e00
	s_addc_u32 s1, s41, 0
	v_writelane_b32 v254, s0, 32
	s_nop 1
	v_writelane_b32 v254, s1, 33
	s_add_u32 s0, s40, 0x1f700f00
	s_addc_u32 s1, s41, 0
	v_writelane_b32 v254, s0, 34
	s_nop 1
	v_writelane_b32 v254, s1, 35
	s_add_u32 s0, s40, 0x1f701000
	s_addc_u32 s1, s41, 0
	v_writelane_b32 v254, s0, 36
	s_nop 1
	v_writelane_b32 v254, s1, 37
	s_add_u32 s0, s40, 0x1f701100
	s_addc_u32 s1, s41, 0
	v_writelane_b32 v254, s0, 38
	s_nop 1
	v_writelane_b32 v254, s1, 39
	s_add_u32 s0, s40, 0x1f701200
	s_addc_u32 s1, s41, 0
	v_writelane_b32 v254, s0, 40
	s_nop 1
	v_writelane_b32 v254, s1, 41
	s_add_u32 s0, s40, 0x1f701300
	s_addc_u32 s1, s41, 0
	v_writelane_b32 v254, s0, 42
	s_nop 1
	v_writelane_b32 v254, s1, 43
	s_add_u32 s0, s40, 0x1f703400
	s_addc_u32 s1, s41, 0
	v_writelane_b32 v254, s0, 44
	s_nop 1
	v_writelane_b32 v254, s1, 45
	s_add_u32 s0, s40, 0x1f703500
	s_addc_u32 s1, s41, 0
	v_writelane_b32 v254, s0, 46
	s_cmpk_lt_i32 s82, 0x680
	s_nop 0
	v_writelane_b32 v254, s1, 47
	s_cselect_b64 s[0:1], -1, 0
	v_writelane_b32 v254, s0, 48
	s_nop 1
	v_writelane_b32 v254, s1, 49
	s_ashr_i32 s0, s82, 31
	v_writelane_b32 v254, s0, 50
	s_lshr_b32 s0, s0, 29
	s_add_i32 s0, s82, s0
	s_ashr_i32 s7, s0, 3
	s_and_b32 s0, s0, -8
	s_sub_i32 s8, s82, s0
	s_ashr_i32 s0, s10, 31
	s_cmpk_lt_i32 s82, 0xc00
	v_writelane_b32 v254, s0, 51
	s_cselect_b64 s[0:1], -1, 0
	v_writelane_b32 v254, s0, 52
	v_writelane_b32 v255, s7, 0
	s_nop 0
	v_writelane_b32 v254, s1, 53
	s_mov_b32 s98, s82
	v_readlane_b32 s99, v254, 5
	s_nop 1
	s_cmp_lg_u32 s99, 0x100
	s_cbranch_scc1 .Lrm_done_a
	s_and_b32 s99, s82, 0xff
	s_lshr_b32 s100, s82, 8
	s_lshr_b32 s101, s100, 2
	s_and_b32 s100, s100, 3
	s_cmp_eq_u32 s101, 1
	s_cbranch_scc1 .Lrm_g1_a
	s_cmp_eq_u32 s101, 2
	s_cbranch_scc1 .Lrm_g2_a
	s_and_b32 s98, s99, 7
	s_lshl_b32 s98, s98, 2
	s_or_b32 s98, s98, s100
	s_branch .Lrm_join_a
.Lrm_g1_a:
	s_bfe_u32 s98, s99, 0x20001
	s_lshl_b32 s100, s100, 2
	s_or_b32 s98, s98, s100
	s_and_b32 s100, s99, 1
	s_lshl_b32 s100, s100, 4
	s_or_b32 s98, s98, s100
	s_branch .Lrm_join_a
.Lrm_g2_a:
	s_and_b32 s98, s99, 7
	s_lshl_b32 s98, s98, 1
	s_lshr_b32 s101, s100, 1
	s_or_b32 s98, s98, s101
	s_and_b32 s100, s100, 1
	s_lshl_b32 s100, s100, 4
	s_or_b32 s98, s98, s100
	s_mov_b32 s101, 2
.Lrm_join_a:
	s_and_b32 s100, s99, 0x38
	s_lshl_b32 s100, s100, 2
	s_or_b32 s98, s98, s100
	s_lshr_b32 s99, s99, 6
	s_mul_i32 s99, s99, 3
	s_add_i32 s99, s99, s101
	s_lshl_b32 s99, s99, 8
	s_or_b32 s98, s98, s99
.Lrm_done_a:
	s_ashr_i32 s1, s98, 8
	s_mul_hi_i32 s2, s1, 0x55555556
	s_lshr_b32 s3, s2, 31
	s_add_i32 s2, s2, s3
	s_mul_i32 s3, s2, 3
	s_and_b32 s0, s98, 31
	s_sub_i32 s1, s1, s3
	s_cmp_eq_u32 s1, 1
	s_cselect_b32 s3, 2, 4
	s_cmp_lg_u32 s1, 0
	s_cselect_b32 s5, s3, 0
	s_lshl_b32 s3, -1, s5
	s_andn2_b32 s14, s0, s3
	s_lshr_b32 s3, s0, s5
	v_writelane_b32 v254, s5, 54
	s_lshl_b32 s3, s3, 7
	v_writelane_b32 v254, s3, 55
	s_addk_i32 s3, 0xff80
	s_lshl_b32 s5, s2, 12
	v_writelane_b32 v254, s3, 56
	s_mul_i32 s2, s2, 0x2400000
	s_mul_i32 s0, s1, 0x600
	s_lshl_b32 s6, s98, 1
	v_writelane_b32 v254, s2, 57
	s_mul_hi_i32 s2, s5, 0x2400
	s_ashr_i32 s1, s0, 31
	s_and_b32 s6, s6, 0x1c0
	v_writelane_b32 v254, s2, 58
	s_cmp_lt_i32 s8, 0
	v_writelane_b32 v254, s14, 59
	s_cselect_b64 s[12:13], -1, 0
	s_movk_i32 s5, 0xd1
	v_writelane_b32 v254, s15, 60
	v_writelane_b32 v254, s12, 61
	s_and_b64 s[2:3], s[12:13], exec
	s_cselect_b32 s2, s5, 0xd0
	s_mul_i32 s2, s8, s2
	s_add_i32 s2, s2, s7
	s_mul_hi_i32 s3, s2, 0x4ec4ec4f
	s_lshr_b32 s5, s3, 31
	s_ashr_i32 s3, s3, 4
	s_add_i32 s3, s3, s5
	s_lshl_b32 s5, s3, 1
	s_mul_i32 s3, s3, 52
	s_sub_i32 s3, s2, s3
	s_bfe_u32 s2, s3, 0x10007
	s_add_i32 s7, s3, s2
	s_bfe_i32 s2, s7, 0x80000
	s_and_b32 s7, s7, 0xfe
	v_writelane_b32 v254, s13, 62
	s_sub_i32 s3, s3, s7
	v_writelane_b32 v254, s8, 63
	s_sext_i32_i16 s8, s2
	s_sext_i32_i8 s3, s3
	s_lshr_b32 s2, s8, 1
	s_add_i32 s14, s5, s3
	s_ashr_i32 s3, s8, 1
	s_abs_i32 s8, s9
	v_cvt_f32_u32_e32 v0, s8
	v_writelane_b32 v255, s3, 1
	s_mov_b32 s12, s14
	s_ashr_i32 s15, s14, 31
	v_rcp_iflag_f32_e32 v0, v0
	v_writelane_b32 v255, s12, 2
	s_bfe_i64 s[2:3], s[2:3], 0x100000
	s_lshl_b64 s[2:3], s[2:3], 19
	v_writelane_b32 v255, s13, 3
	s_lshl_b64 s[12:13], s[14:15], 19
	v_writelane_b32 v255, s12, 4
	v_mul_f32_e32 v0, 0x4f7ffffe, v0
	v_cvt_u32_f32_e32 v0, v0
	v_writelane_b32 v255, s13, 5
	v_writelane_b32 v255, s2, 6
	v_readfirstlane_b32 s5, v0
	s_nop 0
	v_writelane_b32 v255, s3, 7
	s_ashr_i32 s2, s4, 31
	s_bfe_i32 s3, s10, 0x1001c
	v_writelane_b32 v255, s3, 8
	s_xor_b32 s2, s2, s3
	s_sub_i32 s3, 0xffffc001, s9
	s_max_i32 s3, s4, s3
	s_sub_i32 s4, 0, s8
	s_mul_i32 s4, s4, s5
	s_mul_hi_u32 s4, s5, s4
	v_writelane_b32 v255, s9, 9
	s_add_i32 s4, s5, s4
	v_writelane_b32 v255, s4, 10
	s_mul_hi_u32 s4, s3, s4
	s_mul_i32 s5, s4, s8
	s_sub_i32 s3, s3, s5
	s_add_i32 s5, s4, 1
	s_sub_i32 s7, s3, s8
	s_cmp_ge_u32 s3, s8
	s_cselect_b32 s4, s5, s4
	s_cselect_b32 s3, s7, s3
	s_add_i32 s5, s4, 1
	s_cmp_ge_u32 s3, s8
	s_cselect_b32 s3, s5, s4
	s_xor_b32 s3, s3, s2
	v_writelane_b32 v255, s8, 11
	s_sub_i32 s2, s3, s2
	v_writelane_b32 v255, s2, 12
	s_add_i32 s2, s82, s10
	s_lshl_b32 s2, s2, 1
	v_writelane_b32 v255, s2, 13
	s_lshl_b32 s2, s10, 1
	v_writelane_b32 v255, s2, 14
	s_add_i32 s2, 0, 0x20000
	v_writelane_b32 v255, s2, 15
	s_add_i32 s2, 0, 0x20004
	v_writelane_b32 v255, s2, 16
	s_lshl_b64 s[0:1], s[0:1], 1
	v_writelane_b32 v255, s0, 17
	v_mbcnt_lo_u32_b32 v0, -1, 0
	v_mbcnt_hi_u32_b32 v164, -1, v0
	v_writelane_b32 v255, s1, 18
	s_lshl_b32 s0, s6, 1
	v_writelane_b32 v255, s0, 19
	s_add_i32 s0, 0, 0x9000
	v_writelane_b32 v255, s0, 20
	s_mov_b64 s[0:1], 0
	v_writelane_b32 v255, s0, 21
	v_and_b32_e32 v150, 64, v164
	v_add_u32_e32 v165, 64, v150
	v_writelane_b32 v255, s1, 22
	s_mov_b64 s[0:1], -1
	v_writelane_b32 v255, s0, 23
	v_xor_b32_e32 v171, 32, v164
	v_xor_b32_e32 v170, 16, v164
	v_writelane_b32 v255, s1, 24
	v_writelane_b32 v255, s78, 25
	v_xor_b32_e32 v169, 8, v164
	v_xor_b32_e32 v168, 4, v164
	v_writelane_b32 v255, s79, 26
	v_writelane_b32 v255, s82, 27
	v_xor_b32_e32 v167, 2, v164
	v_xor_b32_e32 v166, 1, v164
	v_writelane_b32 v255, s83, 28
	s_branch .LBB0_699

.LBB0_846:
	v_readlane_b32 s2, v254, 5
	s_add_i32 s34, s11, s2
	s_cmpk_gt_i32 s34, 0xbff
	s_cselect_b64 s[52:53], -1, 0
	s_and_b64 vcc, exec, s[52:53]
	s_barrier
	ds_write_b128 v93, v[0:3]
	ds_write_b128 v93, v[4:7] offset:36864
	ds_write_b128 v94, v[8:11]
	ds_write_b128 v94, v[12:15] offset:36864
	ds_write_b128 v95, v[16:19]
	ds_write_b128 v95, v[20:23] offset:36864
	ds_write_b128 v96, v[24:27]
	ds_write_b128 v96, v[28:31] offset:36864
	s_waitcnt lgkmcnt(0)
	s_barrier
	v_readlane_b32 s3, v254, 6
	s_cbranch_vccnz .LBB0_848
	s_mov_b32 s98, s34
	v_readlane_b32 s99, v254, 5
	s_nop 1
	s_cmp_lg_u32 s99, 0x100
	s_cbranch_scc1 .Lrm_done_b
	s_and_b32 s99, s34, 0xff
	s_lshr_b32 s100, s34, 8
	s_lshr_b32 s101, s100, 2
	s_and_b32 s100, s100, 3
	s_cmp_eq_u32 s101, 1
	s_cbranch_scc1 .Lrm_g1_b
	s_cmp_eq_u32 s101, 2
	s_cbranch_scc1 .Lrm_g2_b
	s_and_b32 s98, s99, 7
	s_lshl_b32 s98, s98, 2
	s_or_b32 s98, s98, s100
	s_branch .Lrm_join_b

.Lrm_done_b:
	s_ashr_i32 s3, s98, 8
	s_mul_hi_i32 s35, s3, 0x55555556
	s_lshr_b32 s36, s35, 31
	s_add_i32 s35, s35, s36
	s_mul_i32 s36, s35, 3
	s_and_b32 s2, s98, 31
	s_sub_i32 s3, s3, s36
	s_cmp_eq_u32 s3, 1
	s_cselect_b32 s36, 2, 4
	s_cmp_lg_u32 s3, 0
	s_cselect_b32 s42, s36, 0
	s_lshl_b32 s36, -1, s42
	s_andn2_b32 s36, s2, s36
	s_lshr_b32 s43, s2, s42
	s_lshl_b32 s2, s35, 12
	s_mul_i32 s35, s35, 0x2400000
	s_mul_hi_i32 s2, s2, 0x2400
	s_add_u32 s35, s12, s35
	s_addc_u32 s60, s13, s2
	s_mul_i32 s2, s3, 0x600
	s_ashr_i32 s3, s2, 31
	s_lshl_b64 s[2:3], s[2:3], 1
	s_add_u32 s2, s35, s2
	s_addc_u32 s3, s60, s3
	s_lshl_b32 s99, s98, 1
	s_and_b32 s35, s99, 0x1c0
	s_lshl_b32 s35, s35, 1
	s_add_u32 s2, s2, s35
	s_addc_u32 s3, s3, 0
	s_lshl_b32 s35, s43, 7
	s_add_i32 s43, s35, 0xffffff80
	v_add_u32_e32 v0, s43, v76
	v_max_i32_e32 v128, 0, v0
	v_add_u32_e32 v8, s43, v77
	v_lshlrev_b64 v[0:1], s42, v[128:129]
	v_max_i32_e32 v128, 0, v8
	v_add_u32_e32 v16, s43, v78
	v_lshlrev_b64 v[8:9], s42, v[128:129]
	v_max_i32_e32 v128, 0, v16
	v_add_u32_e32 v24, s43, v79
	v_add_u32_e32 v34, s35, v80
	v_lshlrev_b64 v[16:17], s42, v[128:129]
	v_max_i32_e32 v128, 0, v24
	v_ashrrev_i32_e32 v35, 31, v34
	v_lshlrev_b64 v[24:25], s42, v[128:129]
	v_lshlrev_b64 v[34:35], s42, v[34:35]
	v_lshl_add_u64 v[0:1], v[0:1], 0, s[36:37]
	v_mov_b64_e32 v[32:33], s[2:3]
	v_lshl_add_u64 v[8:9], v[8:9], 0, s[36:37]
	v_lshl_add_u64 v[16:17], v[16:17], 0, s[36:37]
	v_lshl_add_u64 v[24:25], v[24:25], 0, s[36:37]
	v_lshl_add_u64 v[34:35], v[34:35], 0, s[36:37]
	v_mad_u64_u32 v[2:3], s[2:3], v0, s33, v[32:33]
	v_mad_u64_u32 v[10:11], s[2:3], v8, s33, v[32:33]
	v_mad_u64_u32 v[18:19], s[2:3], v16, s33, v[32:33]
	v_mad_u64_u32 v[26:27], s[2:3], v24, s33, v[32:33]
	v_mad_u64_u32 v[32:33], s[2:3], v34, s33, v[32:33]
	v_mad_u32_u24 v3, v1, s33, v3
	v_mov_b32_e32 v59, v129
	v_mad_u32_u24 v11, v9, s33, v11
	v_mad_u32_u24 v19, v17, s33, v19
	v_mad_u32_u24 v27, v25, s33, v27
	v_mad_i32_i24 v33, v35, s33, v33
	v_mov_b32_e32 v61, v129
	v_lshl_add_u64 v[4:5], v[2:3], 0, v[58:59]
	v_lshl_add_u64 v[12:13], v[10:11], 0, v[58:59]
	v_lshl_add_u64 v[20:21], v[18:19], 0, v[58:59]
	v_lshl_add_u64 v[28:29], v[26:27], 0, v[58:59]
	v_lshl_add_u64 v[36:37], v[32:33], 0, v[60:61]
	global_load_dwordx4 v[0:3], v[4:5], off offset:1024
	s_nop 0
	global_load_dwordx4 v[4:7], v[4:5], off offset:2048
	s_nop 0
	global_load_dwordx4 v[8:11], v[12:13], off offset:1024
	s_nop 0
	global_load_dwordx4 v[12:15], v[12:13], off offset:2048
	s_nop 0
	global_load_dwordx4 v[16:19], v[20:21], off offset:1024
	s_nop 0
	global_load_dwordx4 v[20:23], v[20:21], off offset:2048
	s_nop 0
	global_load_dwordx4 v[24:27], v[28:29], off offset:1024
	s_nop 0
	global_load_dwordx4 v[28:31], v[28:29], off offset:2048
	s_nop 0
	global_load_dwordx4 v[32:35], v[36:37], off
	s_nop 0
	global_load_dwordx4 v[36:39], v[36:37], off offset:64
.LBB0_848:
	ds_read_b128 v[48:51], v97
	ds_read_b128 v[52:55], v97 offset:64
	s_mov_b32 s98, s11
	v_readlane_b32 s99, v254, 5
	s_nop 1
	s_cmp_lg_u32 s99, 0x100
	s_cbranch_scc1 .Lrm_done_c
	s_and_b32 s99, s11, 0xff
	s_lshr_b32 s100, s11, 8
	s_lshr_b32 s101, s100, 2
	s_and_b32 s100, s100, 3
	s_cmp_eq_u32 s101, 1
	s_cbranch_scc1 .Lrm_g1_c
	s_cmp_eq_u32 s101, 2
	s_cbranch_scc1 .Lrm_g2_c
	s_and_b32 s98, s99, 7
	s_lshl_b32 s98, s98, 2
	s_or_b32 s98, s98, s100
	s_branch .Lrm_join_c

.Lrm_done_c:
	s_ashr_i32 s2, s98, 8
	s_mul_hi_i32 s3, s2, 0x55555556
	s_lshr_b32 s35, s3, 31
	s_add_i32 s60, s3, s35
	s_mul_i32 s3, s60, 3
	s_and_b32 s61, s98, 31
	s_sub_i32 s68, s2, s3
	s_cmp_eq_u32 s68, 1
	s_waitcnt lgkmcnt(1)
	v_mfma_f32_16x16x32_bf16 v[48:51], v[48:51], v[44:47], 0
	s_cselect_b32 s2, 2, 4
	s_cmp_lg_u32 s68, 0
	s_cselect_b32 s36, s2, 0
	s_lshr_b32 s35, s61, s36
	s_cmp_eq_u32 s35, 0
	s_waitcnt lgkmcnt(0)
	v_mfma_f32_16x16x32_bf16 v[48:51], v[52:55], v[40:43], v[48:51]
	s_cselect_b64 s[2:3], -1, 0
	s_and_b64 s[76:77], s[8:9], s[2:3]
	s_nor_b64 s[82:83], s[6:7], s[76:77]
	v_mov_b32_e32 v59, 0xff800000
	v_mov_b32_e32 v110, 0xff800000
	v_mov_b32_e32 v107, 0xff800000
	v_mov_b32_e32 v52, 0xff800000
	v_mov_b32_e32 v53, 0xff800000
	v_mov_b32_e32 v61, 0xff800000
	s_and_saveexec_b64 s[76:77], s[82:83]
	s_cbranch_execz .LBB0_858
	v_readlane_b32 s42, v255, 32
	v_mul_f32_e32 v107, 0x3e000000, v48
	v_readlane_b32 s43, v255, 33
	s_and_saveexec_b64 s[82:83], s[42:43]
	s_xor_b64 s[82:83], exec, s[82:83]
	s_cbranch_execz .LBB0_855
	v_readlane_b32 s42, v255, 34
	v_readlane_b32 s43, v255, 35
	s_and_saveexec_b64 s[90:91], s[42:43]
	s_xor_b64 s[90:91], exec, s[90:91]
	v_mov_b32_e32 v48, v49
	v_mov_b32_e32 v49, v50
	s_mov_b32 s42, 0x3e000000
	v_pk_mul_f32 v[52:53], v[48:49], s[42:43] op_sel_hi:[1,0]
	s_mov_b32 s42, 0xff800000
	v_max3_f32 v48, v107, s42, v52
	v_mul_f32_e32 v61, 0x3e000000, v51
	v_max3_f32 v110, v48, v53, v61
	s_andn2_saveexec_b64 s[90:91], s[90:91]
	s_cbranch_execz .LBB0_854
	v_mul_f32_e32 v48, 0x3e000000, v49
	v_mul_f32_e32 v49, 0x3e000000, v50
	v_cndmask_b32_e64 v107, v107, v151, s[14:15]
	v_cndmask_b32_e64 v52, v151, v48, s[16:17]
	s_mov_b32 s42, 0xff800000
	v_cndmask_b32_e64 v53, v49, v151, s[18:19]
	v_mul_f32_e32 v49, 0x3e000000, v51
	v_max3_f32 v48, v107, s42, v52
	v_cndmask_b32_e64 v61, v49, v151, s[20:21]
	v_max3_f32 v110, v48, v53, v61

.LBB0_948:
	s_or_b64 exec, exec, s[2:3]
	ds_bpermute_b32 v40, v81, v110
	v_max_f32_e32 v41, v110, v110
	s_lshl_b32 s2, -1, s36
	s_andn2_b32 s82, s61, s2
	s_waitcnt lgkmcnt(0)
	v_max_f32_e32 v40, v40, v40
	v_max_f32_e32 v40, v41, v40
	ds_bpermute_b32 v41, v82, v40
	s_waitcnt lgkmcnt(0)
	v_max_f32_e32 v41, v41, v41
	v_max_f32_e32 v110, v40, v41
	v_sub_f32_e32 v41, v52, v110
	v_sub_f32_e32 v52, v111, v110
	v_mul_f32_e32 v52, 0x3fb8aa3b, v52
	v_sub_f32_e32 v40, v107, v110
	v_exp_f32_e32 v107, v52
	v_sub_f32_e32 v52, v62, v110
	v_mul_f32_e32 v52, 0x3fb8aa3b, v52
	v_sub_f32_e32 v51, v108, v110
	v_exp_f32_e32 v108, v52
	v_sub_f32_e32 v52, v63, v110
	v_mul_f32_e32 v52, 0x3fb8aa3b, v52
	v_exp_f32_e32 v111, v52
	v_sub_f32_e32 v52, v112, v110
	v_mul_f32_e32 v52, 0x3fb8aa3b, v52
	v_exp_f32_e32 v112, v52
	v_sub_f32_e32 v52, v109, v110
	v_mul_f32_e32 v52, 0x3fb8aa3b, v52
	v_exp_f32_e32 v109, v52
	v_sub_f32_e32 v52, v64, v110
	v_mul_f32_e32 v40, 0x3fb8aa3b, v40
	v_mul_f32_e32 v52, 0x3fb8aa3b, v52
	v_exp_f32_e32 v40, v40
	v_mul_f32_e32 v41, 0x3fb8aa3b, v41
	v_exp_f32_e32 v125, v52
	v_sub_f32_e32 v52, v65, v110
	v_exp_f32_e32 v41, v41
	v_mul_f32_e32 v52, 0x3fb8aa3b, v52
	v_exp_f32_e32 v126, v52
	v_sub_f32_e32 v52, v113, v110
	v_mul_f32_e32 v52, 0x3fb8aa3b, v52
	v_add_f32_e32 v42, 0, v40
	v_exp_f32_e32 v113, v52
	v_sub_f32_e32 v52, v115, v110
	v_add_f32_e32 v43, v41, v42
	v_sub_f32_e32 v42, v53, v110
	v_mul_f32_e32 v52, 0x3fb8aa3b, v52
	v_mul_f32_e32 v42, 0x3fb8aa3b, v42
	v_exp_f32_e32 v127, v52
	v_sub_f32_e32 v52, v66, v110
	v_exp_f32_e32 v42, v42
	v_mul_f32_e32 v52, 0x3fb8aa3b, v52
	v_exp_f32_e32 v128, v52
	v_sub_f32_e32 v52, v67, v110
	v_mul_f32_e32 v52, 0x3fb8aa3b, v52
	v_exp_f32_e32 v134, v52
	v_sub_f32_e32 v52, v116, v110
	v_add_f32_e32 v47, v42, v43
	v_sub_f32_e32 v43, v61, v110
	v_mul_f32_e32 v52, 0x3fb8aa3b, v52
	v_mul_f32_e32 v43, 0x3fb8aa3b, v43
	v_sub_f32_e32 v48, v59, v110
	v_exp_f32_e32 v135, v52
	v_sub_f32_e32 v52, v114, v110
	v_exp_f32_e32 v43, v43
	v_mul_f32_e32 v48, 0x3fb8aa3b, v48
	v_sub_f32_e32 v49, v54, v110
	v_mul_f32_e32 v52, 0x3fb8aa3b, v52
	v_exp_f32_e32 v48, v48
	v_mul_f32_e32 v49, 0x3fb8aa3b, v49
	v_sub_f32_e32 v50, v55, v110
	v_exp_f32_e32 v136, v52
	v_sub_f32_e32 v52, v68, v110
	v_exp_f32_e32 v49, v49
	v_mul_f32_e32 v50, 0x3fb8aa3b, v50
	v_mul_f32_e32 v52, 0x3fb8aa3b, v52
	v_exp_f32_e32 v50, v50
	v_mul_f32_e32 v51, 0x3fb8aa3b, v51
	v_exp_f32_e32 v137, v52
	v_sub_f32_e32 v52, v69, v110
	v_add_f32_e32 v47, v43, v47
	v_exp_f32_e32 v51, v51
	v_mul_f32_e32 v52, 0x3fb8aa3b, v52
	v_add_f32_e32 v47, v48, v47
	v_exp_f32_e32 v138, v52
	v_sub_f32_e32 v52, v117, v110
	v_add_f32_e32 v47, v49, v47
	v_mul_f32_e32 v52, 0x3fb8aa3b, v52
	v_add_f32_e32 v47, v50, v47
	v_exp_f32_e32 v139, v52
	v_sub_f32_e32 v52, v119, v110
	v_add_f32_e32 v47, v51, v47
	v_mul_f32_e32 v52, 0x3fb8aa3b, v52
	v_add_f32_e32 v47, v107, v47
	v_exp_f32_e32 v140, v52
	v_sub_f32_e32 v52, v70, v110
	v_add_f32_e32 v47, v108, v47
	v_mul_f32_e32 v52, 0x3fb8aa3b, v52
	v_add_f32_e32 v47, v111, v47
	v_exp_f32_e32 v141, v52
	v_sub_f32_e32 v52, v71, v110
	v_add_f32_e32 v47, v112, v47
	v_mul_f32_e32 v52, 0x3fb8aa3b, v52
	v_add_f32_e32 v47, v109, v47
	v_exp_f32_e32 v142, v52
	v_sub_f32_e32 v52, v120, v110
	v_add_f32_e32 v47, v125, v47
	v_mul_f32_e32 v52, 0x3fb8aa3b, v52
	v_add_f32_e32 v47, v126, v47
	v_exp_f32_e32 v120, v52
	v_sub_f32_e32 v52, v118, v110
	v_add_f32_e32 v47, v113, v47
	v_mul_f32_e32 v52, 0x3fb8aa3b, v52
	v_add_f32_e32 v47, v127, v47
	v_exp_f32_e32 v143, v52
	v_sub_f32_e32 v52, v72, v110
	v_add_f32_e32 v47, v128, v47
	v_mul_f32_e32 v52, 0x3fb8aa3b, v52
	v_add_f32_e32 v47, v134, v47
	v_exp_f32_e32 v144, v52
	v_sub_f32_e32 v52, v73, v110
	v_add_f32_e32 v47, v135, v47
	v_mul_f32_e32 v52, 0x3fb8aa3b, v52
	v_add_f32_e32 v47, v136, v47
	v_exp_f32_e32 v145, v52
	v_sub_f32_e32 v52, v121, v110
	v_add_f32_e32 v47, v137, v47
	v_mul_f32_e32 v52, 0x3fb8aa3b, v52
	v_add_f32_e32 v47, v138, v47
	v_exp_f32_e32 v121, v52
	v_sub_f32_e32 v52, v123, v110
	v_add_f32_e32 v47, v139, v47
	v_mul_f32_e32 v52, 0x3fb8aa3b, v52
	v_add_f32_e32 v47, v140, v47
	v_exp_f32_e32 v123, v52
	v_sub_f32_e32 v52, v74, v110
	v_add_f32_e32 v47, v141, v47
	v_mul_f32_e32 v52, 0x3fb8aa3b, v52
	v_add_f32_e32 v47, v142, v47
	v_exp_f32_e32 v74, v52
	v_sub_f32_e32 v52, v75, v110
	v_add_f32_e32 v47, v120, v47
	v_mul_f32_e32 v52, 0x3fb8aa3b, v52
	v_add_f32_e32 v47, v143, v47
	v_exp_f32_e32 v75, v52
	v_sub_f32_e32 v52, v124, v110
	v_add_f32_e32 v47, v144, v47
	v_mul_f32_e32 v52, 0x3fb8aa3b, v52
	v_add_f32_e32 v47, v145, v47
	v_exp_f32_e32 v124, v52
	v_sub_f32_e32 v52, v122, v110
	v_add_f32_e32 v47, v121, v47
	v_mul_f32_e32 v52, 0x3fb8aa3b, v52
	v_sub_f32_e32 v44, v44, v110
	v_sub_f32_e32 v45, v45, v110
	v_add_f32_e32 v47, v123, v47
	v_exp_f32_e32 v122, v52
	v_mul_f32_e32 v44, 0x3fb8aa3b, v44
	v_mul_f32_e32 v45, 0x3fb8aa3b, v45
	v_add_f32_e32 v47, v74, v47
	v_exp_f32_e32 v153, v44
	v_exp_f32_e32 v154, v45
	v_sub_f32_e32 v45, v46, v110
	v_add_f32_e32 v47, v75, v47
	v_mul_f32_e32 v45, 0x3fb8aa3b, v45
	v_add_f32_e32 v47, v124, v47
	v_exp_f32_e32 v155, v45
	v_add_f32_e32 v47, v122, v47
	v_add_f32_e32 v44, v153, v47
	v_add_f32_e32 v44, v154, v44
	v_add_f32_e32 v44, v155, v44
	ds_bpermute_b32 v45, v81, v44
	v_cvt_pk_bf16_f32 v40, v40, v41
	v_cvt_pk_bf16_f32 v41, v42, v43
	v_cvt_pk_bf16_f32 v42, v48, v49
	v_cvt_pk_bf16_f32 v43, v50, v51
	s_waitcnt lgkmcnt(0)
	v_add_f32_e32 v59, v44, v45
	ds_read_b64_tr_b16 v[62:63], v84
	ds_read_b64_tr_b16 v[52:53], v84 offset:32
	ds_read_b64_tr_b16 v[48:49], v84 offset:64
	ds_read_b64_tr_b16 v[44:45], v84 offset:96
	ds_read_b64_tr_b16 v[64:65], v84 offset:2304
	ds_read_b64_tr_b16 v[54:55], v84 offset:2336
	ds_read_b64_tr_b16 v[50:51], v84 offset:2368
	ds_read_b64_tr_b16 v[46:47], v84 offset:2400
	s_waitcnt lgkmcnt(0)
	ds_bpermute_b32 v61, v82, v59
	v_mfma_f32_16x16x32_bf16 v[62:65], v[40:43], v[62:65], 0
	v_mfma_f32_16x16x32_bf16 v[52:55], v[40:43], v[52:55], 0
	v_mfma_f32_16x16x32_bf16 v[48:51], v[40:43], v[48:51], 0
	v_mfma_f32_16x16x32_bf16 v[40:43], v[40:43], v[44:47], 0
	v_cvt_pk_bf16_f32 v44, v107, v108
	v_cvt_pk_bf16_f32 v45, v111, v112
	v_cvt_pk_bf16_f32 v46, v109, v125
	v_cvt_pk_bf16_f32 v47, v126, v113
	ds_read_b64_tr_b16 v[116:117], v85
	ds_read_b64_tr_b16 v[112:113], v85 offset:32
	ds_read_b64_tr_b16 v[70:71], v85 offset:64
	ds_read_b64_tr_b16 v[66:67], v85 offset:96
	ds_read_b64_tr_b16 v[118:119], v85 offset:2304
	ds_read_b64_tr_b16 v[114:115], v85 offset:2336
	ds_read_b64_tr_b16 v[72:73], v85 offset:2368
	ds_read_b64_tr_b16 v[68:69], v85 offset:2400
	s_waitcnt lgkmcnt(0)
	s_nop 0
	v_mfma_f32_16x16x32_bf16 v[62:65], v[44:47], v[116:119], v[62:65]
	v_mfma_f32_16x16x32_bf16 v[52:55], v[44:47], v[112:115], v[52:55]
	v_mfma_f32_16x16x32_bf16 v[48:51], v[44:47], v[70:73], v[48:51]
	v_mfma_f32_16x16x32_bf16 v[40:43], v[44:47], v[66:69], v[40:43]
	v_cvt_pk_bf16_f32 v44, v127, v128
	v_cvt_pk_bf16_f32 v45, v134, v135
	v_cvt_pk_bf16_f32 v46, v136, v137
	v_cvt_pk_bf16_f32 v47, v138, v139
	ds_read_b64_tr_b16 v[116:117], v86
	ds_read_b64_tr_b16 v[112:113], v86 offset:32
	ds_read_b64_tr_b16 v[70:71], v86 offset:64
	ds_read_b64_tr_b16 v[66:67], v86 offset:96
	ds_read_b64_tr_b16 v[118:119], v86 offset:2304
	ds_read_b64_tr_b16 v[114:115], v86 offset:2336
	ds_read_b64_tr_b16 v[72:73], v86 offset:2368
	ds_read_b64_tr_b16 v[68:69], v86 offset:2400
	s_waitcnt lgkmcnt(0)
	s_nop 0
	v_mfma_f32_16x16x32_bf16 v[62:65], v[44:47], v[116:119], v[62:65]
	v_mfma_f32_16x16x32_bf16 v[52:55], v[44:47], v[112:115], v[52:55]
	v_mfma_f32_16x16x32_bf16 v[48:51], v[44:47], v[70:73], v[48:51]
	v_mfma_f32_16x16x32_bf16 v[40:43], v[44:47], v[66:69], v[40:43]
	v_cvt_pk_bf16_f32 v44, v140, v141
	v_cvt_pk_bf16_f32 v45, v142, v120
	v_cvt_pk_bf16_f32 v46, v143, v144
	v_cvt_pk_bf16_f32 v47, v145, v121
	ds_read_b64_tr_b16 v[116:117], v87
	ds_read_b64_tr_b16 v[112:113], v87 offset:32
	ds_read_b64_tr_b16 v[70:71], v87 offset:64
	ds_read_b64_tr_b16 v[66:67], v87 offset:96
	ds_read_b64_tr_b16 v[118:119], v87 offset:2304
	ds_read_b64_tr_b16 v[114:115], v87 offset:2336
	ds_read_b64_tr_b16 v[72:73], v87 offset:2368
	ds_read_b64_tr_b16 v[68:69], v87 offset:2400
	s_waitcnt lgkmcnt(0)
	s_nop 0
	v_mfma_f32_16x16x32_bf16 v[62:65], v[44:47], v[116:119], v[62:65]
	v_mfma_f32_16x16x32_bf16 v[52:55], v[44:47], v[112:115], v[52:55]
	v_mfma_f32_16x16x32_bf16 v[48:51], v[44:47], v[70:73], v[48:51]
	v_cvt_pk_bf16_f32 v70, v123, v74
	v_cvt_pk_bf16_f32 v71, v75, v124
	v_cvt_pk_bf16_f32 v72, v122, v153
	v_mfma_f32_16x16x32_bf16 v[66:69], v[44:47], v[66:69], v[40:43]
	v_cvt_pk_bf16_f32 v73, v154, v155
	ds_read_b64_tr_b16 v[40:41], v88
	ds_read_b64_tr_b16 v[44:45], v88 offset:32
	ds_read_b64_tr_b16 v[116:117], v88 offset:64
	ds_read_b64_tr_b16 v[112:113], v88 offset:96
	ds_read_b64_tr_b16 v[42:43], v88 offset:2304
	ds_read_b64_tr_b16 v[46:47], v88 offset:2336
	ds_read_b64_tr_b16 v[118:119], v88 offset:2368
	ds_read_b64_tr_b16 v[114:115], v88 offset:2400
	s_waitcnt lgkmcnt(0)
	s_nop 2
	v_mfma_f32_16x16x32_bf16 v[40:43], v[70:73], v[40:43], v[62:65]
	v_mfma_f32_16x16x32_bf16 v[44:47], v[70:73], v[44:47], v[52:55]
	s_nop 1
	v_mov_b64_e32 v[62:63], s[36:37]
	v_mfma_f32_16x16x32_bf16 v[48:51], v[70:73], v[116:119], v[48:51]
	v_mfma_f32_16x16x32_bf16 v[52:55], v[70:73], v[112:115], v[66:69]
	s_and_saveexec_b64 s[42:43], s[4:5]
	s_xor_b64 s[76:77], exec, s[42:43]
	s_ashr_i32 s69, s68, 31
	s_ashr_i32 s61, s60, 31
	s_lshl_b64 s[2:3], s[68:69], 14
	s_lshl_b64 s[42:43], s[60:61], 12
	s_add_u32 s2, s2, s42
	s_addc_u32 s3, s3, s43
	s_or_b32 s2, s2, s82
	v_mov_b64_e32 v[62:63], s[36:37]
	s_or_saveexec_b64 s[76:77], s[76:77]
	s_bfe_u32 s11, s98, 0x30005
	s_waitcnt lgkmcnt(0)
	v_add_f32_e32 v59, v59, v61
	s_lshl_b32 s35, s35, 7
	v_mov_b64_e32 v[64:65], s[2:3]
	s_xor_b64 exec, exec, s[76:77]
	s_cbranch_execz .LBB0_845
	s_mov_b32 s2, 0x800000
	v_cmp_gt_f32_e64 s[2:3], s2, v59
	v_add_u32_e32 v64, s35, v80
	v_ashrrev_i32_e32 v65, 31, v64
	v_cndmask_b32_e64 v61, 0, 32, s[2:3]
	v_ldexp_f32 v61, v59, v61
	v_log_f32_e32 v61, v61
	v_lshlrev_b64 v[64:65], s36, v[64:65]
	s_mov_b32 s36, 0x3f317217
	s_ashr_i32 s69, s68, 31
	v_mul_f32_e32 v63, 0x3f317217, v61
	v_fma_f32 v63, v61, s36, -v63
	v_fmac_f32_e32 v63, 0x3377d1cf, v61
	s_mov_b32 s36, 0x7f800000
	v_fmac_f32_e32 v63, 0x3f317217, v61
	v_cmp_lt_f32_e64 vcc, |v61|, s36
	s_ashr_i32 s61, s60, 31
	s_lshl_b64 s[42:43], s[60:61], 12
	v_cndmask_b32_e32 v61, v61, v63, vcc
	v_cndmask_b32_e64 v63, 0, v152, s[2:3]
	s_lshl_b64 s[2:3], s[68:69], 14
	s_add_u32 s2, s2, s42
	s_addc_u32 s3, s3, s43
	s_or_b32 s2, s2, s82
	v_lshl_add_u64 v[64:65], v[64:65], 0, s[2:3]
	v_lshlrev_b64 v[64:65], 5, v[64:65]
	v_sub_f32_e32 v61, v61, v63
	v_lshl_add_u64 v[64:65], s[0:1], 0, v[64:65]
	s_lshl_b32 s36, s11, 2
	v_add_f32_e32 v61, v110, v61
	v_lshl_add_u64 v[64:65], v[64:65], 0, s[36:37]
	global_store_dword v[64:65], v61, off
	v_mov_b64_e32 v[64:65], s[2:3]
	s_branch .LBB0_845
